# plus write-through stores in the merge phase
# speedup vs baseline: 1.0240x; 1.0008x over previous
.Lmg_nza:
	v_max3_f32 v181, v60, v61, v62
	v_sub_f32_e32 v178, v60, v181
	v_sub_f32_e32 v179, v61, v181
	v_sub_f32_e32 v180, v62, v181
	v_exp_f32_e32 v178, v178
	v_exp_f32_e32 v179, v179
	v_exp_f32_e32 v180, v180
	v_lshlrev_b32_e32 v172, 16, v80
	v_and_b32_e32 v173, s9, v80
	v_lshlrev_b32_e32 v174, 16, v84
	v_and_b32_e32 v175, s9, v84
	v_mul_f32_e32 v148, v172, v174
	v_mul_f32_e32 v149, v173, v175
	v_lshlrev_b32_e32 v172, 16, v81
	v_and_b32_e32 v173, s9, v81
	v_lshlrev_b32_e32 v174, 16, v85
	v_and_b32_e32 v175, s9, v85
	v_mul_f32_e32 v150, v172, v174
	v_mul_f32_e32 v151, v173, v175
	v_lshlrev_b32_e32 v172, 16, v82
	v_and_b32_e32 v173, s9, v82
	v_lshlrev_b32_e32 v174, 16, v86
	v_and_b32_e32 v175, s9, v86
	v_mul_f32_e32 v152, v172, v174
	v_mul_f32_e32 v153, v173, v175
	v_lshlrev_b32_e32 v172, 16, v83
	v_and_b32_e32 v173, s9, v83
	v_lshlrev_b32_e32 v174, 16, v87
	v_and_b32_e32 v175, s9, v87
	v_mul_f32_e32 v154, v172, v174
	v_mul_f32_e32 v155, v173, v175
	v_add_f32_e32 v249, v178, v179
	v_add_f32_e32 v249, v249, v180
	v_rcp_f32_e32 v250, v249
	v_lshlrev_b32_e32 v172, 16, v76
	v_and_b32_e32 v173, s9, v76
	v_mul_f32_e32 v174, v4, v52
	v_fmac_f32_e32 v174, v12, v44
	v_fmac_f32_e32 v174, v20, v148
	v_mul_f32_e32 v164, v172, v174
	v_mul_f32_e32 v253, v164, v164
	v_mul_f32_e32 v175, v5, v53
	v_fmac_f32_e32 v175, v13, v45
	v_fmac_f32_e32 v175, v21, v149
	v_mul_f32_e32 v165, v173, v175
	v_fmac_f32_e32 v253, v165, v165
	v_lshlrev_b32_e32 v172, 16, v77
	v_and_b32_e32 v173, s9, v77
	v_mul_f32_e32 v174, v6, v54
	v_fmac_f32_e32 v174, v14, v46
	v_fmac_f32_e32 v174, v22, v150
	v_mul_f32_e32 v166, v172, v174
	v_fmac_f32_e32 v253, v166, v166
	v_mul_f32_e32 v175, v7, v55
	v_fmac_f32_e32 v175, v15, v47
	v_fmac_f32_e32 v175, v23, v151
	v_mul_f32_e32 v167, v173, v175
	v_fmac_f32_e32 v253, v167, v167
	v_lshlrev_b32_e32 v172, 16, v78
	v_and_b32_e32 v173, s9, v78
	v_mul_f32_e32 v174, v8, v56
	v_fmac_f32_e32 v174, v16, v48
	v_fmac_f32_e32 v174, v24, v152
	v_mul_f32_e32 v168, v172, v174
	v_fmac_f32_e32 v253, v168, v168
	v_mul_f32_e32 v175, v9, v57
	v_fmac_f32_e32 v175, v17, v49
	v_fmac_f32_e32 v175, v25, v153
	v_mul_f32_e32 v169, v173, v175
	v_fmac_f32_e32 v253, v169, v169
	v_lshlrev_b32_e32 v172, 16, v79
	v_and_b32_e32 v173, s9, v79
	v_mul_f32_e32 v174, v10, v58
	v_fmac_f32_e32 v174, v18, v50
	v_fmac_f32_e32 v174, v26, v154
	v_mul_f32_e32 v170, v172, v174
	v_fmac_f32_e32 v253, v170, v170
	v_mul_f32_e32 v175, v11, v59
	v_fmac_f32_e32 v175, v19, v51
	v_fmac_f32_e32 v175, v27, v155
	v_mul_f32_e32 v171, v173, v175
	v_fmac_f32_e32 v253, v171, v171
	v_fma_f32 v251, -v249, v250, 2.0
	v_mul_f32_e32 v250, v250, v251
	v_mul_f32_e32 v178, v178, v250
	v_mul_f32_e32 v179, v179, v250
	v_mul_f32_e32 v180, v180, v250
	v_mov_b32_e32 v52, v44
	v_mov_b32_e32 v53, v45
	v_mov_b32_e32 v54, v46
	v_mov_b32_e32 v55, v47
	v_mov_b32_e32 v56, v48
	v_mov_b32_e32 v57, v49
	v_mov_b32_e32 v58, v50
	v_mov_b32_e32 v59, v51
	v_mov_b32_e32 v44, v148
	v_mov_b32_e32 v45, v149
	v_mov_b32_e32 v46, v150
	v_mov_b32_e32 v47, v151
	v_mov_b32_e32 v48, v152
	v_mov_b32_e32 v49, v153
	v_mov_b32_e32 v50, v154
	v_mov_b32_e32 v51, v155
	v_lshlrev_b32_e32 v172, 16, v64
	v_and_b32_e32 v173, s9, v64
	v_lshlrev_b32_e32 v174, 16, v68
	v_and_b32_e32 v175, s9, v68
	v_lshlrev_b32_e32 v176, 16, v72
	v_and_b32_e32 v177, s9, v72
	v_mul_f32_e32 v156, v178, v172
	v_fmac_f32_e32 v156, v179, v174
	v_fmac_f32_e32 v156, v180, v176
	v_mul_f32_e32 v157, v178, v173
	v_fmac_f32_e32 v157, v179, v175
	v_fmac_f32_e32 v157, v180, v177
	v_mul_f32_e32 v252, v156, v156
	v_fmac_f32_e32 v252, v157, v157
	v_lshlrev_b32_e32 v172, 16, v65
	v_and_b32_e32 v173, s9, v65
	v_lshlrev_b32_e32 v174, 16, v69
	v_and_b32_e32 v175, s9, v69
	v_lshlrev_b32_e32 v176, 16, v73
	v_and_b32_e32 v177, s9, v73
	v_mul_f32_e32 v158, v178, v172
	v_fmac_f32_e32 v158, v179, v174
	v_fmac_f32_e32 v158, v180, v176
	v_mul_f32_e32 v159, v178, v173
	v_fmac_f32_e32 v159, v179, v175
	v_fmac_f32_e32 v159, v180, v177
	v_fmac_f32_e32 v252, v158, v158
	v_fmac_f32_e32 v252, v159, v159
	v_lshlrev_b32_e32 v172, 16, v66
	v_and_b32_e32 v173, s9, v66
	v_lshlrev_b32_e32 v174, 16, v70
	v_and_b32_e32 v175, s9, v70
	v_lshlrev_b32_e32 v176, 16, v74
	v_and_b32_e32 v177, s9, v74
	v_mul_f32_e32 v160, v178, v172
	v_fmac_f32_e32 v160, v179, v174
	v_fmac_f32_e32 v160, v180, v176
	v_mul_f32_e32 v161, v178, v173
	v_fmac_f32_e32 v161, v179, v175
	v_fmac_f32_e32 v161, v180, v177
	v_fmac_f32_e32 v252, v160, v160
	v_fmac_f32_e32 v252, v161, v161
	v_lshlrev_b32_e32 v172, 16, v67
	v_and_b32_e32 v173, s9, v67
	v_lshlrev_b32_e32 v174, 16, v71
	v_and_b32_e32 v175, s9, v71
	v_lshlrev_b32_e32 v176, 16, v75
	v_and_b32_e32 v177, s9, v75
	v_mul_f32_e32 v162, v178, v172
	v_fmac_f32_e32 v162, v179, v174
	v_fmac_f32_e32 v162, v180, v176
	v_mul_f32_e32 v163, v178, v173
	v_fmac_f32_e32 v163, v179, v175
	v_fmac_f32_e32 v163, v180, v177
	v_fmac_f32_e32 v252, v162, v162
	v_fmac_f32_e32 v252, v163, v163
	s_nop 1
	v_add_f32_dpp v252, v252, v252 quad_perm:[1,0,3,2] row_mask:0xf bank_mask:0xf
	v_add_f32_dpp v253, v253, v253 quad_perm:[1,0,3,2] row_mask:0xf bank_mask:0xf
	s_nop 0
	v_add_f32_dpp v252, v252, v252 quad_perm:[2,3,0,1] row_mask:0xf bank_mask:0xf
	v_add_f32_dpp v253, v253, v253 quad_perm:[2,3,0,1] row_mask:0xf bank_mask:0xf
	s_nop 0
	v_add_f32_dpp v252, v252, v252 row_ror:4 row_mask:0xf bank_mask:0xf
	v_add_f32_dpp v253, v253, v253 row_ror:4 row_mask:0xf bank_mask:0xf
	s_nop 0
	v_add_f32_dpp v252, v252, v252 row_ror:8 row_mask:0xf bank_mask:0xf
	v_add_f32_dpp v253, v253, v253 row_ror:8 row_mask:0xf bank_mask:0xf
	s_nop 0
	v_mov_b32_e32 v254, v252
	v_mov_b32_e32 v255, v253
	s_nop 1
	v_permlane16_swap_b32_e32 v252, v254
	v_permlane16_swap_b32_e32 v253, v255
	v_add_f32_e32 v252, v252, v254
	v_add_f32_e32 v253, v253, v255
	v_mov_b32_e32 v254, v252
	v_mov_b32_e32 v255, v253
	s_nop 1
	v_permlane32_swap_b32_e32 v252, v254
	v_permlane32_swap_b32_e32 v253, v255
	v_add_f32_e32 v252, v252, v254
	v_add_f32_e32 v253, v253, v255
	v_fma_f32 v252, v252, s31, v63
	v_fma_f32 v253, v253, s31, v63
	v_rsq_f32_e32 v140, v252
	v_rsq_f32_e32 v141, v253
	v_mul_f32_e32 v252, 0.5, v252
	v_mul_f32_e32 v253, 0.5, v253
	v_mul_f32_e32 v254, v140, v140
	v_mul_f32_e32 v255, v141, v141
	v_fma_f32 v254, -v252, v254, 0.5
	v_fma_f32 v255, -v253, v255, 0.5
	v_fmac_f32_e32 v140, v140, v254
	v_fmac_f32_e32 v141, v141, v255
	v_mul_f32_e32 v156, v156, v140
	v_mul_f32_e32 v164, v164, v141
	v_mul_f32_e32 v156, v156, v28
	v_mul_f32_e32 v164, v164, v36
	v_mul_f32_e32 v157, v157, v140
	v_mul_f32_e32 v165, v165, v141
	v_mul_f32_e32 v157, v157, v29
	v_mul_f32_e32 v165, v165, v37
	v_cvt_pk_bf16_f32 v148, v156, v157
	v_cvt_pk_bf16_f32 v152, v164, v165
	v_mul_f32_e32 v158, v158, v140
	v_mul_f32_e32 v166, v166, v141
	v_mul_f32_e32 v158, v158, v30
	v_mul_f32_e32 v166, v166, v38
	v_mul_f32_e32 v159, v159, v140
	v_mul_f32_e32 v167, v167, v141
	v_mul_f32_e32 v159, v159, v31
	v_mul_f32_e32 v167, v167, v39
	v_cvt_pk_bf16_f32 v149, v158, v159
	v_cvt_pk_bf16_f32 v153, v166, v167
	v_mul_f32_e32 v160, v160, v140
	v_mul_f32_e32 v168, v168, v141
	v_mul_f32_e32 v160, v160, v32
	v_mul_f32_e32 v168, v168, v40
	v_mul_f32_e32 v161, v161, v140
	v_mul_f32_e32 v169, v169, v141
	v_mul_f32_e32 v161, v161, v33
	v_mul_f32_e32 v169, v169, v41
	v_cvt_pk_bf16_f32 v150, v160, v161
	v_cvt_pk_bf16_f32 v154, v168, v169
	v_mul_f32_e32 v162, v162, v140
	v_mul_f32_e32 v170, v170, v141
	v_mul_f32_e32 v162, v162, v34
	v_mul_f32_e32 v170, v170, v42
	v_mul_f32_e32 v163, v163, v140
	v_mul_f32_e32 v171, v171, v141
	v_mul_f32_e32 v163, v163, v35
	v_mul_f32_e32 v171, v171, v43
	v_cvt_pk_bf16_f32 v151, v162, v163
	v_cvt_pk_bf16_f32 v155, v170, v171
	global_store_dwordx4 v0, v[148:151], s[28:29] sc1
	global_store_dwordx4 v0, v[152:155], s[28:29] offset:1024 sc1
	s_add_u32 s28, s28, 0x800
	s_addc_u32 s29, s29, 0
	s_cmp_lt_i32 s30, s3
	s_cbranch_scc0 .Lmg_nl0
	global_load_dword v60, v1, s[4:5] nt
	global_load_dword v61, v1, s[10:11] nt
	global_load_dword v62, v1, s[14:15] nt
	global_load_dwordx4 v[64:67], v0, s[18:19] nt
	global_load_dwordx4 v[68:71], v0, s[20:21] nt
	global_load_dwordx4 v[72:75], v0, s[22:23] nt
	global_load_dwordx4 v[76:79], v0, s[26:27]
	global_load_dwordx4 v[80:83], v0, s[26:27] offset:1024
	global_load_dwordx4 v[84:87], v0, s[26:27] offset:2048
	s_add_u32 s4, s4, 32
	s_addc_u32 s5, s5, 0
	s_add_u32 s10, s10, 32
	s_addc_u32 s11, s11, 0
	s_add_u32 s14, s14, 32
	s_addc_u32 s15, s15, 0
	s_add_u32 s18, s18, 0x400
	s_addc_u32 s19, s19, 0
	s_add_u32 s20, s20, 0x400
	s_addc_u32 s21, s21, 0
	s_add_u32 s22, s22, 0x400
	s_addc_u32 s23, s23, 0
	s_add_u32 s26, s26, 0xc00
	s_addc_u32 s27, s27, 0
	s_add_i32 s30, s30, 1

.Lmg_nzb:
	v_max3_f32 v181, v88, v89, v90
	v_sub_f32_e32 v178, v88, v181
	v_sub_f32_e32 v179, v89, v181
	v_sub_f32_e32 v180, v90, v181
	v_exp_f32_e32 v178, v178
	v_exp_f32_e32 v179, v179
	v_exp_f32_e32 v180, v180
	v_lshlrev_b32_e32 v172, 16, v108
	v_and_b32_e32 v173, s9, v108
	v_lshlrev_b32_e32 v174, 16, v112
	v_and_b32_e32 v175, s9, v112
	v_mul_f32_e32 v148, v172, v174
	v_mul_f32_e32 v149, v173, v175
	v_lshlrev_b32_e32 v172, 16, v109
	v_and_b32_e32 v173, s9, v109
	v_lshlrev_b32_e32 v174, 16, v113
	v_and_b32_e32 v175, s9, v113
	v_mul_f32_e32 v150, v172, v174
	v_mul_f32_e32 v151, v173, v175
	v_lshlrev_b32_e32 v172, 16, v110
	v_and_b32_e32 v173, s9, v110
	v_lshlrev_b32_e32 v174, 16, v114
	v_and_b32_e32 v175, s9, v114
	v_mul_f32_e32 v152, v172, v174
	v_mul_f32_e32 v153, v173, v175
	v_lshlrev_b32_e32 v172, 16, v111
	v_and_b32_e32 v173, s9, v111
	v_lshlrev_b32_e32 v174, 16, v115
	v_and_b32_e32 v175, s9, v115
	v_mul_f32_e32 v154, v172, v174
	v_mul_f32_e32 v155, v173, v175
	v_add_f32_e32 v249, v178, v179
	v_add_f32_e32 v249, v249, v180
	v_rcp_f32_e32 v250, v249
	v_lshlrev_b32_e32 v172, 16, v104
	v_and_b32_e32 v173, s9, v104
	v_mul_f32_e32 v174, v4, v52
	v_fmac_f32_e32 v174, v12, v44
	v_fmac_f32_e32 v174, v20, v148
	v_mul_f32_e32 v164, v172, v174
	v_mul_f32_e32 v253, v164, v164
	v_mul_f32_e32 v175, v5, v53
	v_fmac_f32_e32 v175, v13, v45
	v_fmac_f32_e32 v175, v21, v149
	v_mul_f32_e32 v165, v173, v175
	v_fmac_f32_e32 v253, v165, v165
	v_lshlrev_b32_e32 v172, 16, v105
	v_and_b32_e32 v173, s9, v105
	v_mul_f32_e32 v174, v6, v54
	v_fmac_f32_e32 v174, v14, v46
	v_fmac_f32_e32 v174, v22, v150
	v_mul_f32_e32 v166, v172, v174
	v_fmac_f32_e32 v253, v166, v166
	v_mul_f32_e32 v175, v7, v55
	v_fmac_f32_e32 v175, v15, v47
	v_fmac_f32_e32 v175, v23, v151
	v_mul_f32_e32 v167, v173, v175
	v_fmac_f32_e32 v253, v167, v167
	v_lshlrev_b32_e32 v172, 16, v106
	v_and_b32_e32 v173, s9, v106
	v_mul_f32_e32 v174, v8, v56
	v_fmac_f32_e32 v174, v16, v48
	v_fmac_f32_e32 v174, v24, v152
	v_mul_f32_e32 v168, v172, v174
	v_fmac_f32_e32 v253, v168, v168
	v_mul_f32_e32 v175, v9, v57
	v_fmac_f32_e32 v175, v17, v49
	v_fmac_f32_e32 v175, v25, v153
	v_mul_f32_e32 v169, v173, v175
	v_fmac_f32_e32 v253, v169, v169
	v_lshlrev_b32_e32 v172, 16, v107
	v_and_b32_e32 v173, s9, v107
	v_mul_f32_e32 v174, v10, v58
	v_fmac_f32_e32 v174, v18, v50
	v_fmac_f32_e32 v174, v26, v154
	v_mul_f32_e32 v170, v172, v174
	v_fmac_f32_e32 v253, v170, v170
	v_mul_f32_e32 v175, v11, v59
	v_fmac_f32_e32 v175, v19, v51
	v_fmac_f32_e32 v175, v27, v155
	v_mul_f32_e32 v171, v173, v175
	v_fmac_f32_e32 v253, v171, v171
	v_fma_f32 v251, -v249, v250, 2.0
	v_mul_f32_e32 v250, v250, v251
	v_mul_f32_e32 v178, v178, v250
	v_mul_f32_e32 v179, v179, v250
	v_mul_f32_e32 v180, v180, v250
	v_mov_b32_e32 v52, v44
	v_mov_b32_e32 v53, v45
	v_mov_b32_e32 v54, v46
	v_mov_b32_e32 v55, v47
	v_mov_b32_e32 v56, v48
	v_mov_b32_e32 v57, v49
	v_mov_b32_e32 v58, v50
	v_mov_b32_e32 v59, v51
	v_mov_b32_e32 v44, v148
	v_mov_b32_e32 v45, v149
	v_mov_b32_e32 v46, v150
	v_mov_b32_e32 v47, v151
	v_mov_b32_e32 v48, v152
	v_mov_b32_e32 v49, v153
	v_mov_b32_e32 v50, v154
	v_mov_b32_e32 v51, v155
	v_lshlrev_b32_e32 v172, 16, v92
	v_and_b32_e32 v173, s9, v92
	v_lshlrev_b32_e32 v174, 16, v96
	v_and_b32_e32 v175, s9, v96
	v_lshlrev_b32_e32 v176, 16, v100
	v_and_b32_e32 v177, s9, v100
	v_mul_f32_e32 v156, v178, v172
	v_fmac_f32_e32 v156, v179, v174
	v_fmac_f32_e32 v156, v180, v176
	v_mul_f32_e32 v157, v178, v173
	v_fmac_f32_e32 v157, v179, v175
	v_fmac_f32_e32 v157, v180, v177
	v_mul_f32_e32 v252, v156, v156
	v_fmac_f32_e32 v252, v157, v157
	v_lshlrev_b32_e32 v172, 16, v93
	v_and_b32_e32 v173, s9, v93
	v_lshlrev_b32_e32 v174, 16, v97
	v_and_b32_e32 v175, s9, v97
	v_lshlrev_b32_e32 v176, 16, v101
	v_and_b32_e32 v177, s9, v101
	v_mul_f32_e32 v158, v178, v172
	v_fmac_f32_e32 v158, v179, v174
	v_fmac_f32_e32 v158, v180, v176
	v_mul_f32_e32 v159, v178, v173
	v_fmac_f32_e32 v159, v179, v175
	v_fmac_f32_e32 v159, v180, v177
	v_fmac_f32_e32 v252, v158, v158
	v_fmac_f32_e32 v252, v159, v159
	v_lshlrev_b32_e32 v172, 16, v94
	v_and_b32_e32 v173, s9, v94
	v_lshlrev_b32_e32 v174, 16, v98
	v_and_b32_e32 v175, s9, v98
	v_lshlrev_b32_e32 v176, 16, v102
	v_and_b32_e32 v177, s9, v102
	v_mul_f32_e32 v160, v178, v172
	v_fmac_f32_e32 v160, v179, v174
	v_fmac_f32_e32 v160, v180, v176
	v_mul_f32_e32 v161, v178, v173
	v_fmac_f32_e32 v161, v179, v175
	v_fmac_f32_e32 v161, v180, v177
	v_fmac_f32_e32 v252, v160, v160
	v_fmac_f32_e32 v252, v161, v161
	v_lshlrev_b32_e32 v172, 16, v95
	v_and_b32_e32 v173, s9, v95
	v_lshlrev_b32_e32 v174, 16, v99
	v_and_b32_e32 v175, s9, v99
	v_lshlrev_b32_e32 v176, 16, v103
	v_and_b32_e32 v177, s9, v103
	v_mul_f32_e32 v162, v178, v172
	v_fmac_f32_e32 v162, v179, v174
	v_fmac_f32_e32 v162, v180, v176
	v_mul_f32_e32 v163, v178, v173
	v_fmac_f32_e32 v163, v179, v175
	v_fmac_f32_e32 v163, v180, v177
	v_fmac_f32_e32 v252, v162, v162
	v_fmac_f32_e32 v252, v163, v163
	s_nop 1
	v_add_f32_dpp v252, v252, v252 quad_perm:[1,0,3,2] row_mask:0xf bank_mask:0xf
	v_add_f32_dpp v253, v253, v253 quad_perm:[1,0,3,2] row_mask:0xf bank_mask:0xf
	s_nop 0
	v_add_f32_dpp v252, v252, v252 quad_perm:[2,3,0,1] row_mask:0xf bank_mask:0xf
	v_add_f32_dpp v253, v253, v253 quad_perm:[2,3,0,1] row_mask:0xf bank_mask:0xf
	s_nop 0
	v_add_f32_dpp v252, v252, v252 row_ror:4 row_mask:0xf bank_mask:0xf
	v_add_f32_dpp v253, v253, v253 row_ror:4 row_mask:0xf bank_mask:0xf
	s_nop 0
	v_add_f32_dpp v252, v252, v252 row_ror:8 row_mask:0xf bank_mask:0xf
	v_add_f32_dpp v253, v253, v253 row_ror:8 row_mask:0xf bank_mask:0xf
	s_nop 0
	v_mov_b32_e32 v254, v252
	v_mov_b32_e32 v255, v253
	s_nop 1
	v_permlane16_swap_b32_e32 v252, v254
	v_permlane16_swap_b32_e32 v253, v255
	v_add_f32_e32 v252, v252, v254
	v_add_f32_e32 v253, v253, v255
	v_mov_b32_e32 v254, v252
	v_mov_b32_e32 v255, v253
	s_nop 1
	v_permlane32_swap_b32_e32 v252, v254
	v_permlane32_swap_b32_e32 v253, v255
	v_add_f32_e32 v252, v252, v254
	v_add_f32_e32 v253, v253, v255
	v_fma_f32 v252, v252, s31, v63
	v_fma_f32 v253, v253, s31, v63
	v_rsq_f32_e32 v140, v252
	v_rsq_f32_e32 v141, v253
	v_mul_f32_e32 v252, 0.5, v252
	v_mul_f32_e32 v253, 0.5, v253
	v_mul_f32_e32 v254, v140, v140
	v_mul_f32_e32 v255, v141, v141
	v_fma_f32 v254, -v252, v254, 0.5
	v_fma_f32 v255, -v253, v255, 0.5
	v_fmac_f32_e32 v140, v140, v254
	v_fmac_f32_e32 v141, v141, v255
	v_mul_f32_e32 v156, v156, v140
	v_mul_f32_e32 v164, v164, v141
	v_mul_f32_e32 v156, v156, v28
	v_mul_f32_e32 v164, v164, v36
	v_mul_f32_e32 v157, v157, v140
	v_mul_f32_e32 v165, v165, v141
	v_mul_f32_e32 v157, v157, v29
	v_mul_f32_e32 v165, v165, v37
	v_cvt_pk_bf16_f32 v148, v156, v157
	v_cvt_pk_bf16_f32 v152, v164, v165
	v_mul_f32_e32 v158, v158, v140
	v_mul_f32_e32 v166, v166, v141
	v_mul_f32_e32 v158, v158, v30
	v_mul_f32_e32 v166, v166, v38
	v_mul_f32_e32 v159, v159, v140
	v_mul_f32_e32 v167, v167, v141
	v_mul_f32_e32 v159, v159, v31
	v_mul_f32_e32 v167, v167, v39
	v_cvt_pk_bf16_f32 v149, v158, v159
	v_cvt_pk_bf16_f32 v153, v166, v167
	v_mul_f32_e32 v160, v160, v140
	v_mul_f32_e32 v168, v168, v141
	v_mul_f32_e32 v160, v160, v32
	v_mul_f32_e32 v168, v168, v40
	v_mul_f32_e32 v161, v161, v140
	v_mul_f32_e32 v169, v169, v141
	v_mul_f32_e32 v161, v161, v33
	v_mul_f32_e32 v169, v169, v41
	v_cvt_pk_bf16_f32 v150, v160, v161
	v_cvt_pk_bf16_f32 v154, v168, v169
	v_mul_f32_e32 v162, v162, v140
	v_mul_f32_e32 v170, v170, v141
	v_mul_f32_e32 v162, v162, v34
	v_mul_f32_e32 v170, v170, v42
	v_mul_f32_e32 v163, v163, v140
	v_mul_f32_e32 v171, v171, v141
	v_mul_f32_e32 v163, v163, v35
	v_mul_f32_e32 v171, v171, v43
	v_cvt_pk_bf16_f32 v151, v162, v163
	v_cvt_pk_bf16_f32 v155, v170, v171
	global_store_dwordx4 v0, v[148:151], s[28:29] sc1
	global_store_dwordx4 v0, v[152:155], s[28:29] offset:1024 sc1
	s_add_u32 s28, s28, 0x800
	s_addc_u32 s29, s29, 0
	s_cmp_lt_i32 s30, s3
	s_cbranch_scc0 .Lmg_nl1
	global_load_dword v88, v1, s[4:5] nt
	global_load_dword v89, v1, s[10:11] nt
	global_load_dword v90, v1, s[14:15] nt
	global_load_dwordx4 v[92:95], v0, s[18:19] nt
	global_load_dwordx4 v[96:99], v0, s[20:21] nt
	global_load_dwordx4 v[100:103], v0, s[22:23] nt
	global_load_dwordx4 v[104:107], v0, s[26:27]
	global_load_dwordx4 v[108:111], v0, s[26:27] offset:1024
	global_load_dwordx4 v[112:115], v0, s[26:27] offset:2048
	s_add_u32 s4, s4, 32
	s_addc_u32 s5, s5, 0
	s_add_u32 s10, s10, 32
	s_addc_u32 s11, s11, 0
	s_add_u32 s14, s14, 32
	s_addc_u32 s15, s15, 0
	s_add_u32 s18, s18, 0x400
	s_addc_u32 s19, s19, 0
	s_add_u32 s20, s20, 0x400
	s_addc_u32 s21, s21, 0
	s_add_u32 s22, s22, 0x400
	s_addc_u32 s23, s23, 0
	s_add_u32 s26, s26, 0xc00
	s_addc_u32 s27, s27, 0
	s_add_i32 s30, s30, 1

.Lmg_nzc:
	v_max3_f32 v181, v116, v117, v118
	v_sub_f32_e32 v178, v116, v181
	v_sub_f32_e32 v179, v117, v181
	v_sub_f32_e32 v180, v118, v181
	v_exp_f32_e32 v178, v178
	v_exp_f32_e32 v179, v179
	v_exp_f32_e32 v180, v180
	v_lshlrev_b32_e32 v172, 16, v136
	v_and_b32_e32 v173, s9, v136
	v_lshlrev_b32_e32 v174, 16, v144
	v_and_b32_e32 v175, s9, v144
	v_mul_f32_e32 v148, v172, v174
	v_mul_f32_e32 v149, v173, v175
	v_lshlrev_b32_e32 v172, 16, v137
	v_and_b32_e32 v173, s9, v137
	v_lshlrev_b32_e32 v174, 16, v145
	v_and_b32_e32 v175, s9, v145
	v_mul_f32_e32 v150, v172, v174
	v_mul_f32_e32 v151, v173, v175
	v_lshlrev_b32_e32 v172, 16, v138
	v_and_b32_e32 v173, s9, v138
	v_lshlrev_b32_e32 v174, 16, v146
	v_and_b32_e32 v175, s9, v146
	v_mul_f32_e32 v152, v172, v174
	v_mul_f32_e32 v153, v173, v175
	v_lshlrev_b32_e32 v172, 16, v139
	v_and_b32_e32 v173, s9, v139
	v_lshlrev_b32_e32 v174, 16, v147
	v_and_b32_e32 v175, s9, v147
	v_mul_f32_e32 v154, v172, v174
	v_mul_f32_e32 v155, v173, v175
	v_add_f32_e32 v249, v178, v179
	v_add_f32_e32 v249, v249, v180
	v_rcp_f32_e32 v250, v249
	v_lshlrev_b32_e32 v172, 16, v132
	v_and_b32_e32 v173, s9, v132
	v_mul_f32_e32 v174, v4, v52
	v_fmac_f32_e32 v174, v12, v44
	v_fmac_f32_e32 v174, v20, v148
	v_mul_f32_e32 v164, v172, v174
	v_mul_f32_e32 v253, v164, v164
	v_mul_f32_e32 v175, v5, v53
	v_fmac_f32_e32 v175, v13, v45
	v_fmac_f32_e32 v175, v21, v149
	v_mul_f32_e32 v165, v173, v175
	v_fmac_f32_e32 v253, v165, v165
	v_lshlrev_b32_e32 v172, 16, v133
	v_and_b32_e32 v173, s9, v133
	v_mul_f32_e32 v174, v6, v54
	v_fmac_f32_e32 v174, v14, v46
	v_fmac_f32_e32 v174, v22, v150
	v_mul_f32_e32 v166, v172, v174
	v_fmac_f32_e32 v253, v166, v166
	v_mul_f32_e32 v175, v7, v55
	v_fmac_f32_e32 v175, v15, v47
	v_fmac_f32_e32 v175, v23, v151
	v_mul_f32_e32 v167, v173, v175
	v_fmac_f32_e32 v253, v167, v167
	v_lshlrev_b32_e32 v172, 16, v134
	v_and_b32_e32 v173, s9, v134
	v_mul_f32_e32 v174, v8, v56
	v_fmac_f32_e32 v174, v16, v48
	v_fmac_f32_e32 v174, v24, v152
	v_mul_f32_e32 v168, v172, v174
	v_fmac_f32_e32 v253, v168, v168
	v_mul_f32_e32 v175, v9, v57
	v_fmac_f32_e32 v175, v17, v49
	v_fmac_f32_e32 v175, v25, v153
	v_mul_f32_e32 v169, v173, v175
	v_fmac_f32_e32 v253, v169, v169
	v_lshlrev_b32_e32 v172, 16, v135
	v_and_b32_e32 v173, s9, v135
	v_mul_f32_e32 v174, v10, v58
	v_fmac_f32_e32 v174, v18, v50
	v_fmac_f32_e32 v174, v26, v154
	v_mul_f32_e32 v170, v172, v174
	v_fmac_f32_e32 v253, v170, v170
	v_mul_f32_e32 v175, v11, v59
	v_fmac_f32_e32 v175, v19, v51
	v_fmac_f32_e32 v175, v27, v155
	v_mul_f32_e32 v171, v173, v175
	v_fmac_f32_e32 v253, v171, v171
	v_fma_f32 v251, -v249, v250, 2.0
	v_mul_f32_e32 v250, v250, v251
	v_mul_f32_e32 v178, v178, v250
	v_mul_f32_e32 v179, v179, v250
	v_mul_f32_e32 v180, v180, v250
	v_mov_b32_e32 v52, v44
	v_mov_b32_e32 v53, v45
	v_mov_b32_e32 v54, v46
	v_mov_b32_e32 v55, v47
	v_mov_b32_e32 v56, v48
	v_mov_b32_e32 v57, v49
	v_mov_b32_e32 v58, v50
	v_mov_b32_e32 v59, v51
	v_mov_b32_e32 v44, v148
	v_mov_b32_e32 v45, v149
	v_mov_b32_e32 v46, v150
	v_mov_b32_e32 v47, v151
	v_mov_b32_e32 v48, v152
	v_mov_b32_e32 v49, v153
	v_mov_b32_e32 v50, v154
	v_mov_b32_e32 v51, v155
	v_lshlrev_b32_e32 v172, 16, v120
	v_and_b32_e32 v173, s9, v120
	v_lshlrev_b32_e32 v174, 16, v124
	v_and_b32_e32 v175, s9, v124
	v_lshlrev_b32_e32 v176, 16, v128
	v_and_b32_e32 v177, s9, v128
	v_mul_f32_e32 v156, v178, v172
	v_fmac_f32_e32 v156, v179, v174
	v_fmac_f32_e32 v156, v180, v176
	v_mul_f32_e32 v157, v178, v173
	v_fmac_f32_e32 v157, v179, v175
	v_fmac_f32_e32 v157, v180, v177
	v_mul_f32_e32 v252, v156, v156
	v_fmac_f32_e32 v252, v157, v157
	v_lshlrev_b32_e32 v172, 16, v121
	v_and_b32_e32 v173, s9, v121
	v_lshlrev_b32_e32 v174, 16, v125
	v_and_b32_e32 v175, s9, v125
	v_lshlrev_b32_e32 v176, 16, v129
	v_and_b32_e32 v177, s9, v129
	v_mul_f32_e32 v158, v178, v172
	v_fmac_f32_e32 v158, v179, v174
	v_fmac_f32_e32 v158, v180, v176
	v_mul_f32_e32 v159, v178, v173
	v_fmac_f32_e32 v159, v179, v175
	v_fmac_f32_e32 v159, v180, v177
	v_fmac_f32_e32 v252, v158, v158
	v_fmac_f32_e32 v252, v159, v159
	v_lshlrev_b32_e32 v172, 16, v122
	v_and_b32_e32 v173, s9, v122
	v_lshlrev_b32_e32 v174, 16, v126
	v_and_b32_e32 v175, s9, v126
	v_lshlrev_b32_e32 v176, 16, v130
	v_and_b32_e32 v177, s9, v130
	v_mul_f32_e32 v160, v178, v172
	v_fmac_f32_e32 v160, v179, v174
	v_fmac_f32_e32 v160, v180, v176
	v_mul_f32_e32 v161, v178, v173
	v_fmac_f32_e32 v161, v179, v175
	v_fmac_f32_e32 v161, v180, v177
	v_fmac_f32_e32 v252, v160, v160
	v_fmac_f32_e32 v252, v161, v161
	v_lshlrev_b32_e32 v172, 16, v123
	v_and_b32_e32 v173, s9, v123
	v_lshlrev_b32_e32 v174, 16, v127
	v_and_b32_e32 v175, s9, v127
	v_lshlrev_b32_e32 v176, 16, v131
	v_and_b32_e32 v177, s9, v131
	v_mul_f32_e32 v162, v178, v172
	v_fmac_f32_e32 v162, v179, v174
	v_fmac_f32_e32 v162, v180, v176
	v_mul_f32_e32 v163, v178, v173
	v_fmac_f32_e32 v163, v179, v175
	v_fmac_f32_e32 v163, v180, v177
	v_fmac_f32_e32 v252, v162, v162
	v_fmac_f32_e32 v252, v163, v163
	s_nop 1
	v_add_f32_dpp v252, v252, v252 quad_perm:[1,0,3,2] row_mask:0xf bank_mask:0xf
	v_add_f32_dpp v253, v253, v253 quad_perm:[1,0,3,2] row_mask:0xf bank_mask:0xf
	s_nop 0
	v_add_f32_dpp v252, v252, v252 quad_perm:[2,3,0,1] row_mask:0xf bank_mask:0xf
	v_add_f32_dpp v253, v253, v253 quad_perm:[2,3,0,1] row_mask:0xf bank_mask:0xf
	s_nop 0
	v_add_f32_dpp v252, v252, v252 row_ror:4 row_mask:0xf bank_mask:0xf
	v_add_f32_dpp v253, v253, v253 row_ror:4 row_mask:0xf bank_mask:0xf
	s_nop 0
	v_add_f32_dpp v252, v252, v252 row_ror:8 row_mask:0xf bank_mask:0xf
	v_add_f32_dpp v253, v253, v253 row_ror:8 row_mask:0xf bank_mask:0xf
	s_nop 0
	v_mov_b32_e32 v254, v252
	v_mov_b32_e32 v255, v253
	s_nop 1
	v_permlane16_swap_b32_e32 v252, v254
	v_permlane16_swap_b32_e32 v253, v255
	v_add_f32_e32 v252, v252, v254
	v_add_f32_e32 v253, v253, v255
	v_mov_b32_e32 v254, v252
	v_mov_b32_e32 v255, v253
	s_nop 1
	v_permlane32_swap_b32_e32 v252, v254
	v_permlane32_swap_b32_e32 v253, v255
	v_add_f32_e32 v252, v252, v254
	v_add_f32_e32 v253, v253, v255
	v_fma_f32 v252, v252, s31, v63
	v_fma_f32 v253, v253, s31, v63
	v_rsq_f32_e32 v140, v252
	v_rsq_f32_e32 v141, v253
	v_mul_f32_e32 v252, 0.5, v252
	v_mul_f32_e32 v253, 0.5, v253
	v_mul_f32_e32 v254, v140, v140
	v_mul_f32_e32 v255, v141, v141
	v_fma_f32 v254, -v252, v254, 0.5
	v_fma_f32 v255, -v253, v255, 0.5
	v_fmac_f32_e32 v140, v140, v254
	v_fmac_f32_e32 v141, v141, v255
	v_mul_f32_e32 v156, v156, v140
	v_mul_f32_e32 v164, v164, v141
	v_mul_f32_e32 v156, v156, v28
	v_mul_f32_e32 v164, v164, v36
	v_mul_f32_e32 v157, v157, v140
	v_mul_f32_e32 v165, v165, v141
	v_mul_f32_e32 v157, v157, v29
	v_mul_f32_e32 v165, v165, v37
	v_cvt_pk_bf16_f32 v148, v156, v157
	v_cvt_pk_bf16_f32 v152, v164, v165
	v_mul_f32_e32 v158, v158, v140
	v_mul_f32_e32 v166, v166, v141
	v_mul_f32_e32 v158, v158, v30
	v_mul_f32_e32 v166, v166, v38
	v_mul_f32_e32 v159, v159, v140
	v_mul_f32_e32 v167, v167, v141
	v_mul_f32_e32 v159, v159, v31
	v_mul_f32_e32 v167, v167, v39
	v_cvt_pk_bf16_f32 v149, v158, v159
	v_cvt_pk_bf16_f32 v153, v166, v167
	v_mul_f32_e32 v160, v160, v140
	v_mul_f32_e32 v168, v168, v141
	v_mul_f32_e32 v160, v160, v32
	v_mul_f32_e32 v168, v168, v40
	v_mul_f32_e32 v161, v161, v140
	v_mul_f32_e32 v169, v169, v141
	v_mul_f32_e32 v161, v161, v33
	v_mul_f32_e32 v169, v169, v41
	v_cvt_pk_bf16_f32 v150, v160, v161
	v_cvt_pk_bf16_f32 v154, v168, v169
	v_mul_f32_e32 v162, v162, v140
	v_mul_f32_e32 v170, v170, v141
	v_mul_f32_e32 v162, v162, v34
	v_mul_f32_e32 v170, v170, v42
	v_mul_f32_e32 v163, v163, v140
	v_mul_f32_e32 v171, v171, v141
	v_mul_f32_e32 v163, v163, v35
	v_mul_f32_e32 v171, v171, v43
	v_cvt_pk_bf16_f32 v151, v162, v163
	v_cvt_pk_bf16_f32 v155, v170, v171
	global_store_dwordx4 v0, v[148:151], s[28:29] sc1
	global_store_dwordx4 v0, v[152:155], s[28:29] offset:1024 sc1
	s_add_u32 s28, s28, 0x800
	s_addc_u32 s29, s29, 0
	s_cmp_lt_i32 s30, s3
	s_cbranch_scc0 .Lmg_nl2
	global_load_dword v116, v1, s[4:5] nt
	global_load_dword v117, v1, s[10:11] nt
	global_load_dword v118, v1, s[14:15] nt
	global_load_dwordx4 v[120:123], v0, s[18:19] nt
	global_load_dwordx4 v[124:127], v0, s[20:21] nt
	global_load_dwordx4 v[128:131], v0, s[22:23] nt
	global_load_dwordx4 v[132:135], v0, s[26:27]
	global_load_dwordx4 v[136:139], v0, s[26:27] offset:1024
	global_load_dwordx4 v[144:147], v0, s[26:27] offset:2048
	s_add_u32 s4, s4, 32
	s_addc_u32 s5, s5, 0
	s_add_u32 s10, s10, 32
	s_addc_u32 s11, s11, 0
	s_add_u32 s14, s14, 32
	s_addc_u32 s15, s15, 0
	s_add_u32 s18, s18, 0x400
	s_addc_u32 s19, s19, 0
	s_add_u32 s20, s20, 0x400
	s_addc_u32 s21, s21, 0
	s_add_u32 s22, s22, 0x400
	s_addc_u32 s23, s23, 0
	s_add_u32 s26, s26, 0xc00
	s_addc_u32 s27, s27, 0
	s_add_i32 s30, s30, 1
